# P3 fused epilogue: 16 of the 32 x-tile loads issued before the 4-workgroup row-norm exchange and consumed after it; rest pipelined; waits count loads only
# speedup vs baseline: 1.0021x; 1.0021x over previous
;     __device__ __forceinline__ bool run(const f32x4 (&v)[2][2][4][2], const Unit& u, int wr, int wc, int fr, int fq, PG8_LAS unsigned char* lds, int wid, int lane) const {
;     ...
; #pragma unroll
;         for (int ai = 0; ai < 2; ++ai)
; #pragma unroll
;             for (int m = 0; m < 4; ++m) {
;                 float s = 0.f;
; #pragma unroll
;                 for (int bj = 0; bj < 2; ++bj)
; #pragma unroll
;                     for (int n = 0; n < 2; ++n) { const f32x4 x = v[ai][bj][m][n]; s += (x[0] * x[0] + x[1] * x[1]) + (x[2] * x[2] + x[3] * x[3]); }
;                 { auto rr = __builtin_amdgcn_permlane16_swap(__float_as_uint(s), __float_as_uint(s), false, false); s = __uint_as_float(rr[0]) + __uint_as_float(rr[1]); }
;                 { auto rr = __builtin_amdgcn_permlane32_swap(__float_as_uint(s), __float_as_uint(s), false, false); s = __uint_as_float(rr[0]) + __uint_as_float(rr[1]); }
;                 if (fq == 0) P[(ai * HALF + wr * 64 + m * 16 + fr) * 4 + wc] = s;
;             }
;     __device__ __forceinline__ void fused(f32x4 (&acc)[2][2][4][2], const Unit& u, int wr, int wc, int fr, int fq, PG8_LAS unsigned char* lds, int wid, int lane) const {
;     ...
;         const int col0 = u.pn * BM + wc * 32 + 4 * fq;
;         f32x4 gv[2][2];
; #pragma unroll
;         for (int bj = 0; bj < 2; ++bj)
; #pragma unroll
;             for (int n = 0; n < 2; ++n) gv[bj][n] = *(const f32x4*)(g + col0 + bj * HALF + n * 16);
;         const bool bad = st.run(acc, u, wr, wc, fr, fq, lds, wid, lane);
;         const float qnan = __builtin_nanf("");
;         const float* xb = (u.pm < 64) ? (x_p + (size_t)u.pm * BM * 1024) : (x_s + (size_t)(u.pm - 64) * BM * 1024);
.LBB0_1159:
	s_lshl_b32 s0, s24, 5
	s_lshl_b32 s1, s20, 8
	s_or_b32 s0, s0, s1
	v_lshrrev_b32_e32 v126, 2, v0
	v_and_or_b32 v126, v126, 12, s0
	v_lshlrev_b32_e32 v150, 2, v126
	s_barrier
	global_load_dwordx4 v[142:145], v150, s[88:89]
	global_load_dwordx4 v[138:141], v150, s[88:89] offset:64
	global_load_dwordx4 v[134:137], v150, s[88:89] offset:512
	global_load_dwordx4 v[126:129], v150, s[88:89] offset:576
	s_add_i32 s42, s8, -64
	v_readlane_b32 s28, v253, 7
	v_readlane_b32 s29, v253, 8
	v_readlane_b32 s30, v253, 9
	v_readlane_b32 s31, v253, 10
	s_cmp_gt_i32 s8, 63
	s_cselect_b32 s28, s30, s28
	s_cselect_b32 s29, s31, s29
	s_cselect_b32 s42, s42, s8
	s_lshl_b32 s42, s42, 20
	s_add_u32 s28, s28, s42
	s_addc_u32 s29, s29, 0
	v_lshlrev_b32_e32 v163, 12, v146
	v_or_b32_e32 v163, v163, v150
	s_add_u32 s30, s28, 0x10000
	s_addc_u32 s31, s29, 0
	s_add_u32 s32, s28, 0x20000
	s_addc_u32 s33, s29, 0
	s_add_u32 s34, s28, 0x30000
	s_addc_u32 s35, s29, 0
	s_add_u32 s36, s28, 0x80000
	s_addc_u32 s37, s29, 0
	s_add_u32 s38, s28, 0x90000
	s_addc_u32 s39, s29, 0
	s_add_u32 s40, s28, 0xa0000
	s_addc_u32 s41, s29, 0
	s_add_u32 s42, s28, 0xb0000
	s_addc_u32 s43, s29, 0
	global_load_dwordx4 v[164:167], v163, s[28:29]
	global_load_dwordx4 v[168:171], v163, s[28:29] offset:64
	global_load_dwordx4 v[172:175], v163, s[28:29] offset:512
	global_load_dwordx4 v[176:179], v163, s[28:29] offset:576
	global_load_dwordx4 v[180:183], v163, s[30:31]
	global_load_dwordx4 v[184:187], v163, s[30:31] offset:64
	global_load_dwordx4 v[188:191], v163, s[30:31] offset:512
	global_load_dwordx4 v[192:195], v163, s[30:31] offset:576
	global_load_dwordx4 v[196:199], v163, s[32:33]
	global_load_dwordx4 v[200:203], v163, s[32:33] offset:64
	global_load_dwordx4 v[204:207], v163, s[32:33] offset:512
	global_load_dwordx4 v[208:211], v163, s[32:33] offset:576
	global_load_dwordx4 v[212:215], v163, s[34:35]
	global_load_dwordx4 v[216:219], v163, s[34:35] offset:64
	global_load_dwordx4 v[220:223], v163, s[34:35] offset:512
	global_load_dwordx4 v[224:227], v163, s[34:35] offset:576
	v_mul_f32_e32 v148, v131, v131
	v_mul_f32_e32 v149, v133, v133
	v_fmac_f32_e32 v148, v130, v130
	v_fmac_f32_e32 v149, v132, v132
	v_add_f32_e32 v148, v148, v149
	v_mul_f32_e32 v149, v123, v123
	v_mul_f32_e32 v151, v125, v125
	v_fmac_f32_e32 v149, v122, v122
	v_fmac_f32_e32 v151, v124, v124
	v_add_f32_e32 v149, v149, v151
	v_add_f32_e32 v148, v148, v149
	v_mul_f32_e32 v149, v119, v119
	v_mul_f32_e32 v151, v121, v121
	v_fmac_f32_e32 v149, v118, v118
	v_fmac_f32_e32 v151, v120, v120
	v_add_f32_e32 v149, v149, v151
	v_add_f32_e32 v148, v148, v149
	v_mul_f32_e32 v149, v111, v111
	v_mul_f32_e32 v151, v113, v113
	v_fmac_f32_e32 v149, v110, v110
	v_fmac_f32_e32 v151, v112, v112
	v_add_f32_e32 v149, v149, v151
	v_add_f32_e32 v148, v148, v149
	v_mov_b32_e32 v149, v148
	s_nop 1
	v_permlane16_swap_b32_e32 v148, v149
	v_add_f32_e32 v148, v148, v149
	v_and_b32_e32 v147, 63, v0
	s_lshl_b32 s0, s24, 2
	v_mov_b32_e32 v149, v148
	v_cmp_gt_u32_e32 vcc, 16, v147
	s_add_i32 s2, s0, 0
	v_permlane32_swap_b32_e32 v148, v149
	s_and_saveexec_b64 s[0:1], vcc
	s_lshl_b32 s3, s21, 10
	s_add_i32 s3, s2, s3
	v_lshl_add_u32 v151, v1, 4, s3
	v_add_f32_e32 v148, v148, v149
	ds_write_b32 v151, v148
	s_or_b64 exec, exec, s[0:1]
	v_mul_f32_e32 v148, v115, v115
	v_mul_f32_e32 v149, v117, v117
	v_fmac_f32_e32 v148, v114, v114
	v_fmac_f32_e32 v149, v116, v116
	v_add_f32_e32 v148, v148, v149
	v_mul_f32_e32 v149, v107, v107
	v_mul_f32_e32 v151, v109, v109
	v_fmac_f32_e32 v149, v106, v106
	v_fmac_f32_e32 v151, v108, v108
	v_add_f32_e32 v149, v149, v151
	v_add_f32_e32 v148, v148, v149
	v_mul_f32_e32 v149, v103, v103
	v_mul_f32_e32 v151, v105, v105
	v_fmac_f32_e32 v149, v102, v102
	v_fmac_f32_e32 v151, v104, v104
	v_add_f32_e32 v149, v149, v151
	v_add_f32_e32 v148, v148, v149
	v_mul_f32_e32 v149, v95, v95
	v_mul_f32_e32 v151, v97, v97
	v_fmac_f32_e32 v149, v94, v94
	v_fmac_f32_e32 v151, v96, v96
	v_add_f32_e32 v149, v149, v151
	v_add_f32_e32 v148, v148, v149
	v_mov_b32_e32 v149, v148
	s_nop 1
	v_permlane16_swap_b32_e32 v148, v149
	v_add_f32_e32 v148, v148, v149
	v_mov_b32_e32 v149, v148
	s_nop 1
	v_permlane32_swap_b32_e32 v148, v149
	s_and_saveexec_b64 s[0:1], vcc
	s_lshl_b32 s3, s21, 10
	s_add_i32 s3, s2, s3
	v_lshl_add_u32 v151, v1, 4, s3
	v_add_f32_e32 v148, v148, v149
	ds_write_b32 v151, v148 offset:256
	s_or_b64 exec, exec, s[0:1]
	v_mul_f32_e32 v148, v99, v99
	v_mul_f32_e32 v149, v101, v101
	v_fmac_f32_e32 v148, v98, v98
	v_fmac_f32_e32 v149, v100, v100
	v_add_f32_e32 v148, v148, v149
	v_mul_f32_e32 v149, v91, v91
	v_mul_f32_e32 v151, v93, v93
	v_fmac_f32_e32 v149, v90, v90
	v_fmac_f32_e32 v151, v92, v92
	v_add_f32_e32 v149, v149, v151
	v_add_f32_e32 v148, v148, v149
	v_mul_f32_e32 v149, v87, v87
	v_mul_f32_e32 v151, v89, v89
	v_fmac_f32_e32 v149, v86, v86
	v_fmac_f32_e32 v151, v88, v88
	v_add_f32_e32 v149, v149, v151
	v_add_f32_e32 v148, v148, v149
	v_mul_f32_e32 v149, v79, v79
	v_mul_f32_e32 v151, v81, v81
	v_fmac_f32_e32 v149, v78, v78
	v_fmac_f32_e32 v151, v80, v80
	v_add_f32_e32 v149, v149, v151
	v_add_f32_e32 v148, v148, v149
	v_mov_b32_e32 v149, v148
	s_nop 1
	v_permlane16_swap_b32_e32 v148, v149
	v_add_f32_e32 v148, v148, v149
	v_mov_b32_e32 v149, v148
	s_nop 1
	v_permlane32_swap_b32_e32 v148, v149
	s_and_saveexec_b64 s[0:1], vcc
	s_lshl_b32 s3, s21, 10
	s_add_i32 s3, s2, s3
	v_lshl_add_u32 v151, v1, 4, s3
	v_add_f32_e32 v148, v148, v149
	ds_write_b32 v151, v148 offset:512
	s_or_b64 exec, exec, s[0:1]
	v_mul_f32_e32 v148, v83, v83
	v_mul_f32_e32 v149, v85, v85
	v_fmac_f32_e32 v148, v82, v82
	v_fmac_f32_e32 v149, v84, v84
	v_add_f32_e32 v148, v148, v149
;     __device__ __forceinline__ bool run(const f32x4 (&v)[2][2][4][2], const Unit& u, int wr, int wc, int fr, int fq, PG8_LAS unsigned char* lds, int wid, int lane) const {
;     ...
; #pragma unroll
;         for (int ai = 0; ai < 2; ++ai)
; #pragma unroll
;             for (int m = 0; m < 4; ++m) {
;                 float s = 0.f;
; #pragma unroll
;                 for (int bj = 0; bj < 2; ++bj)
; #pragma unroll
;                     for (int n = 0; n < 2; ++n) { const f32x4 x = v[ai][bj][m][n]; s += (x[0] * x[0] + x[1] * x[1]) + (x[2] * x[2] + x[3] * x[3]); }
;                 { auto rr = __builtin_amdgcn_permlane16_swap(__float_as_uint(s), __float_as_uint(s), false, false); s = __uint_as_float(rr[0]) + __uint_as_float(rr[1]); }
;                 { auto rr = __builtin_amdgcn_permlane32_swap(__float_as_uint(s), __float_as_uint(s), false, false); s = __uint_as_float(rr[0]) + __uint_as_float(rr[1]); }
;                 if (fq == 0) P[(ai * HALF + wr * 64 + m * 16 + fr) * 4 + wc] = s;
;             }
;         asm volatile("s_waitcnt lgkmcnt(0)" ::: "memory"); __builtin_amdgcn_s_barrier(); asm volatile("" ::: "memory");
;         const int row = wid * 32 + (lane & 31);
;         if (lane < 32) {
;             const float t = (P[row * 4 + 0] + P[row * 4 + 1]) + (P[row * 4 + 2] + P[row * 4 + 3]);
;             __hip_atomic_store(xbuf + ((size_t)(u.pm * BM + row) * 4 + u.pn), __float_as_uint(t), __ATOMIC_RELAXED, __HIP_MEMORY_SCOPE_AGENT);
	v_mul_f32_e32 v149, v75, v75
	v_mul_f32_e32 v151, v77, v77
	v_fmac_f32_e32 v149, v74, v74
	v_fmac_f32_e32 v151, v76, v76
	v_add_f32_e32 v149, v149, v151
	v_add_f32_e32 v148, v148, v149
	v_mul_f32_e32 v149, v71, v71
	v_mul_f32_e32 v151, v73, v73
	v_fmac_f32_e32 v149, v70, v70
	v_fmac_f32_e32 v151, v72, v72
	v_add_f32_e32 v149, v149, v151
	v_add_f32_e32 v148, v148, v149
	v_mul_f32_e32 v149, v67, v67
	v_mul_f32_e32 v151, v69, v69
	v_fmac_f32_e32 v149, v66, v66
	v_fmac_f32_e32 v151, v68, v68
	v_add_f32_e32 v149, v149, v151
	v_add_f32_e32 v148, v148, v149
	v_mov_b32_e32 v149, v148
	s_nop 1
	v_permlane16_swap_b32_e32 v148, v149
	v_add_f32_e32 v148, v148, v149
	v_mov_b32_e32 v149, v148
	s_nop 1
	v_permlane32_swap_b32_e32 v148, v149
	s_and_saveexec_b64 s[0:1], vcc
	s_lshl_b32 s3, s21, 10
	s_add_i32 s3, s2, s3
	v_lshl_add_u32 v151, v1, 4, s3
	v_add_f32_e32 v148, v148, v149
	ds_write_b32 v151, v148 offset:768
	s_or_b64 exec, exec, s[0:1]
	v_mul_f32_e32 v148, v63, v63
	v_mul_f32_e32 v149, v65, v65
	v_fmac_f32_e32 v148, v62, v62
	v_fmac_f32_e32 v149, v64, v64
	v_add_f32_e32 v148, v148, v149
	v_mul_f32_e32 v149, v59, v59
	v_mul_f32_e32 v151, v61, v61
	v_fmac_f32_e32 v149, v58, v58
	v_fmac_f32_e32 v151, v60, v60
	v_add_f32_e32 v149, v149, v151
	v_add_f32_e32 v148, v148, v149
	v_mul_f32_e32 v149, v55, v55
	v_mul_f32_e32 v151, v57, v57
	v_fmac_f32_e32 v149, v54, v54
	v_fmac_f32_e32 v151, v56, v56
	v_add_f32_e32 v149, v149, v151
	v_add_f32_e32 v148, v148, v149
	v_mul_f32_e32 v149, v47, v47
	v_mul_f32_e32 v151, v49, v49
	v_fmac_f32_e32 v149, v46, v46
	v_fmac_f32_e32 v151, v48, v48
	v_add_f32_e32 v149, v149, v151
	v_add_f32_e32 v148, v148, v149
	v_mov_b32_e32 v149, v148
	s_nop 1
	v_permlane16_swap_b32_e32 v148, v149
	v_add_f32_e32 v148, v148, v149
	v_mov_b32_e32 v149, v148
	s_nop 1
	v_permlane32_swap_b32_e32 v148, v149
	s_and_saveexec_b64 s[0:1], vcc
	s_lshl_b32 s3, s21, 10
	s_add_i32 s3, s2, s3
	v_lshl_add_u32 v151, v1, 4, s3
	v_add_f32_e32 v148, v148, v149
	ds_write_b32 v151, v148 offset:2048
	s_or_b64 exec, exec, s[0:1]
	v_mul_f32_e32 v148, v51, v51
	v_mul_f32_e32 v149, v53, v53
	v_fmac_f32_e32 v148, v50, v50
	v_fmac_f32_e32 v149, v52, v52
	v_add_f32_e32 v148, v148, v149
	v_mul_f32_e32 v149, v43, v43
	v_mul_f32_e32 v151, v45, v45
	v_fmac_f32_e32 v149, v42, v42
	v_fmac_f32_e32 v151, v44, v44
	v_add_f32_e32 v149, v149, v151
	v_add_f32_e32 v148, v148, v149
	v_mul_f32_e32 v149, v39, v39
	v_mul_f32_e32 v151, v41, v41
	v_fmac_f32_e32 v149, v38, v38
	v_fmac_f32_e32 v151, v40, v40
	v_add_f32_e32 v149, v149, v151
	v_add_f32_e32 v148, v148, v149
	v_mul_f32_e32 v149, v31, v31
	v_mul_f32_e32 v151, v33, v33
	v_fmac_f32_e32 v149, v30, v30
	v_fmac_f32_e32 v151, v32, v32
	v_add_f32_e32 v149, v149, v151
	v_add_f32_e32 v148, v148, v149
	v_mov_b32_e32 v149, v148
	s_nop 1
	v_permlane16_swap_b32_e32 v148, v149
	v_add_f32_e32 v148, v148, v149
	v_mov_b32_e32 v149, v148
	s_nop 1
	v_permlane32_swap_b32_e32 v148, v149
	s_and_saveexec_b64 s[0:1], vcc
	s_lshl_b32 s3, s21, 10
	s_add_i32 s3, s2, s3
	v_lshl_add_u32 v151, v1, 4, s3
	v_add_f32_e32 v148, v148, v149
	ds_write_b32 v151, v148 offset:2304
	s_or_b64 exec, exec, s[0:1]
	v_mul_f32_e32 v148, v35, v35
	v_mul_f32_e32 v149, v37, v37
	v_fmac_f32_e32 v148, v34, v34
	v_fmac_f32_e32 v149, v36, v36
	v_add_f32_e32 v148, v148, v149
	v_mul_f32_e32 v149, v27, v27
	v_mul_f32_e32 v151, v29, v29
	v_fmac_f32_e32 v149, v26, v26
	v_fmac_f32_e32 v151, v28, v28
	v_add_f32_e32 v149, v149, v151
	v_add_f32_e32 v148, v148, v149
	v_mul_f32_e32 v149, v23, v23
	v_mul_f32_e32 v151, v25, v25
	v_fmac_f32_e32 v149, v22, v22
	v_fmac_f32_e32 v151, v24, v24
	v_add_f32_e32 v149, v149, v151
	v_add_f32_e32 v148, v148, v149
	v_mul_f32_e32 v149, v15, v15
	v_mul_f32_e32 v151, v17, v17
	v_fmac_f32_e32 v149, v14, v14
	v_fmac_f32_e32 v151, v16, v16
	v_add_f32_e32 v149, v149, v151
	v_add_f32_e32 v148, v148, v149
	v_mov_b32_e32 v149, v148
	s_nop 1
	v_permlane16_swap_b32_e32 v148, v149
	v_add_f32_e32 v148, v148, v149
	v_mov_b32_e32 v149, v148
	s_nop 1
	v_permlane32_swap_b32_e32 v148, v149
	s_and_saveexec_b64 s[0:1], vcc
	s_lshl_b32 s3, s21, 10
	s_add_i32 s3, s2, s3
	v_lshl_add_u32 v151, v1, 4, s3
	v_add_f32_e32 v148, v148, v149
	ds_write_b32 v151, v148 offset:2560
	s_or_b64 exec, exec, s[0:1]
	v_mul_f32_e32 v148, v19, v19
	v_mul_f32_e32 v149, v21, v21
	v_fmac_f32_e32 v148, v18, v18
	v_fmac_f32_e32 v149, v20, v20
	v_add_f32_e32 v148, v148, v149
	v_mul_f32_e32 v149, v11, v11
	v_mul_f32_e32 v151, v13, v13
	v_fmac_f32_e32 v149, v10, v10
	v_fmac_f32_e32 v151, v12, v12
	v_add_f32_e32 v149, v149, v151
	v_add_f32_e32 v148, v148, v149
	v_mul_f32_e32 v149, v7, v7
	v_mul_f32_e32 v151, v9, v9
	v_fmac_f32_e32 v149, v6, v6
	v_fmac_f32_e32 v151, v8, v8
	v_add_f32_e32 v149, v149, v151
	v_add_f32_e32 v148, v148, v149
	v_mul_f32_e32 v149, v3, v3
	v_mul_f32_e32 v151, v5, v5
	v_fmac_f32_e32 v149, v2, v2
	v_fmac_f32_e32 v151, v4, v4
	v_add_f32_e32 v149, v149, v151
	v_add_f32_e32 v148, v148, v149
	v_mov_b32_e32 v149, v148
	s_nop 1
	v_permlane16_swap_b32_e32 v148, v149
	v_add_f32_e32 v148, v148, v149
	v_mov_b32_e32 v149, v148
	s_nop 1
	v_permlane32_swap_b32_e32 v148, v149
	s_and_saveexec_b64 s[0:1], vcc
	s_lshl_b32 s3, s21, 10
	s_add_i32 s2, s2, s3
	v_lshl_add_u32 v1, v1, 4, s2
	v_add_f32_e32 v148, v148, v149
	ds_write_b32 v1, v148 offset:2816
	s_or_b64 exec, exec, s[0:1]
	s_waitcnt lgkmcnt(0)
	s_barrier
	v_and_b32_e32 v0, 31, v0
	v_lshl_or_b32 v151, s19, 5, v0
	v_cmp_gt_u32_e64 s[0:1], 32, v147
	v_lshl_add_u32 v0, s8, 8, v151
	s_and_saveexec_b64 s[2:3], s[0:1]
	s_cbranch_execz .LBB0_1177
	v_lshl_add_u32 v1, v151, 4, 0
	ds_read_b128 v[152:155], v1
	v_ashrrev_i32_e32 v1, 31, v0
	s_mov_b32 s5, 0
	s_lshl_b32 s4, s20, 2
	s_waitcnt lgkmcnt(0)
	v_mov_b32_e32 v148, v153
	v_mov_b32_e32 v149, v154
	v_mov_b32_e32 v153, v155
	v_pk_add_f32 v[148:149], v[148:149], v[152:153]
	v_lshl_add_u64 v[152:153], v[0:1], 4, s[6:7]
	v_pk_add_f32 v[148:149], v[148:149], v[148:149] op_sel:[0,1] op_sel_hi:[1,0]
	v_lshl_add_u64 v[152:153], v[152:153], 0, s[4:5]
	global_store_dword v[152:153], v148, off sc1

;     __device__ __forceinline__ void fused(f32x4 (&acc)[2][2][4][2], const Unit& u, int wr, int wc, int fr, int fq, PG8_LAS unsigned char* lds, int wid, int lane) const {
;     ...
;         const float qnan = __builtin_nanf("");
;         const float* xb = (u.pm < 64) ? (x_p + (size_t)u.pm * BM * 1024) : (x_s + (size_t)(u.pm - 64) * BM * 1024);
;         float* ob = out + (size_t)u.pm * BM * 1024;
; #pragma unroll
;         for (int ai = 0; ai < 2; ++ai)
; #pragma unroll
;             for (int m = 0; m < 4; ++m) { const int r = ai * HALF + wr * 64 + m * 16 + fr; const float rs = S[r]; const size_t off = (size_t)r * 1024 + col0;
; #pragma unroll
;                 for (int bj = 0; bj < 2; ++bj)
; #pragma unroll
;                     for (int n = 0; n < 2; ++n) { const f32x4 xv = *(const f32x4*)(xb + off + bj * HALF + n * 16); f32x4 o = xv + acc[ai][bj][m][n] * rs * gv[bj][n];
.LBB0_1203:
	v_lshl_add_u32 v147, v146, 2, 0
	v_add_u32_e32 v148, 0x2000, v147
	ds_read_b32 v236, v148
	ds_read_b32 v238, v148 offset:64
	ds_read_b32 v240, v148 offset:128
	ds_read_b32 v242, v148 offset:192
	ds_read_b32 v244, v148 offset:512
	ds_read_b32 v246, v148 offset:576
	ds_read_b32 v248, v148 offset:640
	ds_read_b32 v250, v148 offset:704
	s_add_u32 s2, s92, s2
	s_addc_u32 s3, s93, s3
	s_add_u32 s44, s2, 0x10000
	s_addc_u32 s45, s3, 0
	s_add_u32 s46, s2, 0x20000
	s_addc_u32 s47, s3, 0
	s_add_u32 s48, s2, 0x30000
	s_addc_u32 s49, s3, 0
	s_add_u32 s50, s2, 0x80000
	s_addc_u32 s51, s3, 0
	s_add_u32 s52, s2, 0x90000
	s_addc_u32 s53, s3, 0
	s_add_u32 s54, s2, 0xa0000
	s_addc_u32 s55, s3, 0
	s_add_u32 s56, s2, 0xb0000
	s_addc_u32 s57, s3, 0
	global_load_dwordx4 v[228:231], v163, s[36:37]
	global_load_dwordx4 v[232:235], v163, s[36:37] offset:64
	v_mov_b32_e32 v147, 0x7fc00000
	v_cmp_eq_u32_e32 vcc, 0, v149
	s_waitcnt lgkmcnt(7)
	v_pk_mul_f32 v[130:131], v[130:131], v[236:237] op_sel_hi:[1,0]
	v_pk_mul_f32 v[132:133], v[132:133], v[236:237] op_sel_hi:[1,0]
	v_pk_mul_f32 v[122:123], v[122:123], v[236:237] op_sel_hi:[1,0]
	v_pk_mul_f32 v[124:125], v[124:125], v[236:237] op_sel_hi:[1,0]
	v_pk_mul_f32 v[118:119], v[118:119], v[236:237] op_sel_hi:[1,0]
	v_pk_mul_f32 v[120:121], v[120:121], v[236:237] op_sel_hi:[1,0]
	v_pk_mul_f32 v[110:111], v[110:111], v[236:237] op_sel_hi:[1,0]
	v_pk_mul_f32 v[112:113], v[112:113], v[236:237] op_sel_hi:[1,0]
	s_waitcnt lgkmcnt(6)
	v_pk_mul_f32 v[114:115], v[114:115], v[238:239] op_sel_hi:[1,0]
	v_pk_mul_f32 v[116:117], v[116:117], v[238:239] op_sel_hi:[1,0]
	v_pk_mul_f32 v[106:107], v[106:107], v[238:239] op_sel_hi:[1,0]
	v_pk_mul_f32 v[108:109], v[108:109], v[238:239] op_sel_hi:[1,0]
	v_pk_mul_f32 v[102:103], v[102:103], v[238:239] op_sel_hi:[1,0]
	v_pk_mul_f32 v[104:105], v[104:105], v[238:239] op_sel_hi:[1,0]
	v_pk_mul_f32 v[94:95], v[94:95], v[238:239] op_sel_hi:[1,0]
	v_pk_mul_f32 v[96:97], v[96:97], v[238:239] op_sel_hi:[1,0]
	s_waitcnt lgkmcnt(5)
	v_pk_mul_f32 v[98:99], v[98:99], v[240:241] op_sel_hi:[1,0]
	v_pk_mul_f32 v[100:101], v[100:101], v[240:241] op_sel_hi:[1,0]
	v_pk_mul_f32 v[90:91], v[90:91], v[240:241] op_sel_hi:[1,0]
	v_pk_mul_f32 v[92:93], v[92:93], v[240:241] op_sel_hi:[1,0]
	v_pk_mul_f32 v[86:87], v[86:87], v[240:241] op_sel_hi:[1,0]
	v_pk_mul_f32 v[88:89], v[88:89], v[240:241] op_sel_hi:[1,0]
	v_pk_mul_f32 v[78:79], v[78:79], v[240:241] op_sel_hi:[1,0]
	v_pk_mul_f32 v[80:81], v[80:81], v[240:241] op_sel_hi:[1,0]
	s_waitcnt lgkmcnt(4)
	v_pk_mul_f32 v[82:83], v[82:83], v[242:243] op_sel_hi:[1,0]
	v_pk_mul_f32 v[84:85], v[84:85], v[242:243] op_sel_hi:[1,0]
	v_pk_mul_f32 v[74:75], v[74:75], v[242:243] op_sel_hi:[1,0]
	v_pk_mul_f32 v[76:77], v[76:77], v[242:243] op_sel_hi:[1,0]
	v_pk_mul_f32 v[70:71], v[70:71], v[242:243] op_sel_hi:[1,0]
	v_pk_mul_f32 v[72:73], v[72:73], v[242:243] op_sel_hi:[1,0]
	v_pk_mul_f32 v[66:67], v[66:67], v[242:243] op_sel_hi:[1,0]
	v_pk_mul_f32 v[68:69], v[68:69], v[242:243] op_sel_hi:[1,0]
	s_waitcnt lgkmcnt(3)
	v_pk_mul_f32 v[62:63], v[62:63], v[244:245] op_sel_hi:[1,0]
	v_pk_mul_f32 v[64:65], v[64:65], v[244:245] op_sel_hi:[1,0]
	v_pk_mul_f32 v[58:59], v[58:59], v[244:245] op_sel_hi:[1,0]
	v_pk_mul_f32 v[60:61], v[60:61], v[244:245] op_sel_hi:[1,0]
	v_pk_mul_f32 v[54:55], v[54:55], v[244:245] op_sel_hi:[1,0]
	v_pk_mul_f32 v[56:57], v[56:57], v[244:245] op_sel_hi:[1,0]
	v_pk_mul_f32 v[46:47], v[46:47], v[244:245] op_sel_hi:[1,0]
	v_pk_mul_f32 v[48:49], v[48:49], v[244:245] op_sel_hi:[1,0]
	s_waitcnt lgkmcnt(2)
	v_pk_mul_f32 v[50:51], v[50:51], v[246:247] op_sel_hi:[1,0]
	v_pk_mul_f32 v[52:53], v[52:53], v[246:247] op_sel_hi:[1,0]
	v_pk_mul_f32 v[42:43], v[42:43], v[246:247] op_sel_hi:[1,0]
	v_pk_mul_f32 v[44:45], v[44:45], v[246:247] op_sel_hi:[1,0]
	v_pk_mul_f32 v[38:39], v[38:39], v[246:247] op_sel_hi:[1,0]
	v_pk_mul_f32 v[40:41], v[40:41], v[246:247] op_sel_hi:[1,0]
	v_pk_mul_f32 v[30:31], v[30:31], v[246:247] op_sel_hi:[1,0]
	v_pk_mul_f32 v[32:33], v[32:33], v[246:247] op_sel_hi:[1,0]
	s_waitcnt lgkmcnt(1)
	v_pk_mul_f32 v[34:35], v[34:35], v[248:249] op_sel_hi:[1,0]
	v_pk_mul_f32 v[36:37], v[36:37], v[248:249] op_sel_hi:[1,0]
	v_pk_mul_f32 v[26:27], v[26:27], v[248:249] op_sel_hi:[1,0]
	v_pk_mul_f32 v[28:29], v[28:29], v[248:249] op_sel_hi:[1,0]
	v_pk_mul_f32 v[22:23], v[22:23], v[248:249] op_sel_hi:[1,0]
	v_pk_mul_f32 v[24:25], v[24:25], v[248:249] op_sel_hi:[1,0]
	v_pk_mul_f32 v[14:15], v[14:15], v[248:249] op_sel_hi:[1,0]
	v_pk_mul_f32 v[16:17], v[16:17], v[248:249] op_sel_hi:[1,0]
	s_waitcnt lgkmcnt(0)
	v_pk_mul_f32 v[18:19], v[18:19], v[250:251] op_sel_hi:[1,0]
	v_pk_mul_f32 v[20:21], v[20:21], v[250:251] op_sel_hi:[1,0]
	v_pk_mul_f32 v[10:11], v[10:11], v[250:251] op_sel_hi:[1,0]
	v_pk_mul_f32 v[12:13], v[12:13], v[250:251] op_sel_hi:[1,0]
	v_pk_mul_f32 v[6:7], v[6:7], v[250:251] op_sel_hi:[1,0]
	v_pk_mul_f32 v[8:9], v[8:9], v[250:251] op_sel_hi:[1,0]
	v_pk_mul_f32 v[2:3], v[2:3], v[250:251] op_sel_hi:[1,0]
	v_pk_mul_f32 v[4:5], v[4:5], v[250:251] op_sel_hi:[1,0]
	s_waitcnt vmcnt(2)
;     __device__ __forceinline__ void fused(f32x4 (&acc)[2][2][4][2], const Unit& u, int wr, int wc, int fr, int fq, PG8_LAS unsigned char* lds, int wid, int lane) const {
;     ...
; #pragma unroll
;         for (int ai = 0; ai < 2; ++ai)
; #pragma unroll
;             for (int m = 0; m < 4; ++m) { const int r = ai * HALF + wr * 64 + m * 16 + fr; const float rs = S[r]; const size_t off = (size_t)r * 1024 + col0;
; #pragma unroll
;                 for (int bj = 0; bj < 2; ++bj)
; #pragma unroll
;                     for (int n = 0; n < 2; ++n) { const f32x4 xv = *(const f32x4*)(xb + off + bj * HALF + n * 16); f32x4 o = xv + acc[ai][bj][m][n] * rs * gv[bj][n];
;                         if (bad) o = (f32x4){qnan, qnan, qnan, qnan}; *(f32x4*)(ob + off + bj * HALF + n * 16) = o; }
;                 if (m & 1) asm volatile("" ::: "memory"); }
	v_pk_fma_f32 v[130:131], v[142:143], v[130:131], v[164:165]
	v_pk_fma_f32 v[132:133], v[144:145], v[132:133], v[166:167]
	v_cndmask_b32_e32 v130, v147, v130, vcc
	v_cndmask_b32_e32 v131, v147, v131, vcc
	v_cndmask_b32_e32 v132, v147, v132, vcc
	v_cndmask_b32_e32 v133, v147, v133, vcc
	global_store_dwordx4 v163, v[130:133], s[2:3]
	global_load_dwordx4 v[164:167], v163, s[36:37] offset:512
	v_pk_fma_f32 v[122:123], v[138:139], v[122:123], v[168:169]
	v_pk_fma_f32 v[124:125], v[140:141], v[124:125], v[170:171]
	v_cndmask_b32_e32 v122, v147, v122, vcc
	v_cndmask_b32_e32 v123, v147, v123, vcc
	v_cndmask_b32_e32 v124, v147, v124, vcc
	v_cndmask_b32_e32 v125, v147, v125, vcc
	global_store_dwordx4 v163, v[122:125], s[2:3] offset:64
	global_load_dwordx4 v[168:171], v163, s[36:37] offset:576
	v_pk_fma_f32 v[118:119], v[134:135], v[118:119], v[172:173]
	v_pk_fma_f32 v[120:121], v[136:137], v[120:121], v[174:175]
	v_cndmask_b32_e32 v118, v147, v118, vcc
	v_cndmask_b32_e32 v119, v147, v119, vcc
	v_cndmask_b32_e32 v120, v147, v120, vcc
	v_cndmask_b32_e32 v121, v147, v121, vcc
	global_store_dwordx4 v163, v[118:121], s[2:3] offset:512
	global_load_dwordx4 v[172:175], v163, s[38:39]
	v_pk_fma_f32 v[110:111], v[126:127], v[110:111], v[176:177]
	v_pk_fma_f32 v[112:113], v[128:129], v[112:113], v[178:179]
	v_cndmask_b32_e32 v110, v147, v110, vcc
	v_cndmask_b32_e32 v111, v147, v111, vcc
	v_cndmask_b32_e32 v112, v147, v112, vcc
	v_cndmask_b32_e32 v113, v147, v113, vcc
	global_store_dwordx4 v163, v[110:113], s[2:3] offset:576
	global_load_dwordx4 v[176:179], v163, s[38:39] offset:64
	v_pk_fma_f32 v[114:115], v[142:143], v[114:115], v[180:181]
	v_pk_fma_f32 v[116:117], v[144:145], v[116:117], v[182:183]
	v_cndmask_b32_e32 v114, v147, v114, vcc
	v_cndmask_b32_e32 v115, v147, v115, vcc
	v_cndmask_b32_e32 v116, v147, v116, vcc
	v_cndmask_b32_e32 v117, v147, v117, vcc
	global_store_dwordx4 v163, v[114:117], s[44:45]
	global_load_dwordx4 v[180:183], v163, s[38:39] offset:512
	v_pk_fma_f32 v[106:107], v[138:139], v[106:107], v[184:185]
	v_pk_fma_f32 v[108:109], v[140:141], v[108:109], v[186:187]
	v_cndmask_b32_e32 v106, v147, v106, vcc
	v_cndmask_b32_e32 v107, v147, v107, vcc
	v_cndmask_b32_e32 v108, v147, v108, vcc
	v_cndmask_b32_e32 v109, v147, v109, vcc
	global_store_dwordx4 v163, v[106:109], s[44:45] offset:64
	global_load_dwordx4 v[184:187], v163, s[38:39] offset:576
	v_pk_fma_f32 v[102:103], v[134:135], v[102:103], v[188:189]
	v_pk_fma_f32 v[104:105], v[136:137], v[104:105], v[190:191]
	v_cndmask_b32_e32 v102, v147, v102, vcc
	v_cndmask_b32_e32 v103, v147, v103, vcc
	v_cndmask_b32_e32 v104, v147, v104, vcc
	v_cndmask_b32_e32 v105, v147, v105, vcc
	global_store_dwordx4 v163, v[102:105], s[44:45] offset:512
	global_load_dwordx4 v[188:191], v163, s[40:41]
	v_pk_fma_f32 v[94:95], v[126:127], v[94:95], v[192:193]
	v_pk_fma_f32 v[96:97], v[128:129], v[96:97], v[194:195]
	v_cndmask_b32_e32 v94, v147, v94, vcc
	v_cndmask_b32_e32 v95, v147, v95, vcc
	v_cndmask_b32_e32 v96, v147, v96, vcc
	v_cndmask_b32_e32 v97, v147, v97, vcc
	global_store_dwordx4 v163, v[94:97], s[44:45] offset:576
	global_load_dwordx4 v[192:195], v163, s[40:41] offset:64
	v_pk_fma_f32 v[98:99], v[142:143], v[98:99], v[196:197]
	v_pk_fma_f32 v[100:101], v[144:145], v[100:101], v[198:199]
	v_cndmask_b32_e32 v98, v147, v98, vcc
	v_cndmask_b32_e32 v99, v147, v99, vcc
	v_cndmask_b32_e32 v100, v147, v100, vcc
	v_cndmask_b32_e32 v101, v147, v101, vcc
	global_store_dwordx4 v163, v[98:101], s[46:47]
	global_load_dwordx4 v[196:199], v163, s[40:41] offset:512
	v_pk_fma_f32 v[90:91], v[138:139], v[90:91], v[200:201]
	v_pk_fma_f32 v[92:93], v[140:141], v[92:93], v[202:203]
	v_cndmask_b32_e32 v90, v147, v90, vcc
	v_cndmask_b32_e32 v91, v147, v91, vcc
	v_cndmask_b32_e32 v92, v147, v92, vcc
	v_cndmask_b32_e32 v93, v147, v93, vcc
	global_store_dwordx4 v163, v[90:93], s[46:47] offset:64
	global_load_dwordx4 v[200:203], v163, s[40:41] offset:576
	v_pk_fma_f32 v[86:87], v[134:135], v[86:87], v[204:205]
	v_pk_fma_f32 v[88:89], v[136:137], v[88:89], v[206:207]
	v_cndmask_b32_e32 v86, v147, v86, vcc
	v_cndmask_b32_e32 v87, v147, v87, vcc
	v_cndmask_b32_e32 v88, v147, v88, vcc
	v_cndmask_b32_e32 v89, v147, v89, vcc
	global_store_dwordx4 v163, v[86:89], s[46:47] offset:512
	global_load_dwordx4 v[204:207], v163, s[42:43]
	v_pk_fma_f32 v[78:79], v[126:127], v[78:79], v[208:209]
	v_pk_fma_f32 v[80:81], v[128:129], v[80:81], v[210:211]
	v_cndmask_b32_e32 v78, v147, v78, vcc
	v_cndmask_b32_e32 v79, v147, v79, vcc
	v_cndmask_b32_e32 v80, v147, v80, vcc
	v_cndmask_b32_e32 v81, v147, v81, vcc
	global_store_dwordx4 v163, v[78:81], s[46:47] offset:576
	global_load_dwordx4 v[208:211], v163, s[42:43] offset:64
	v_pk_fma_f32 v[82:83], v[142:143], v[82:83], v[212:213]
	v_pk_fma_f32 v[84:85], v[144:145], v[84:85], v[214:215]
	v_cndmask_b32_e32 v82, v147, v82, vcc
	v_cndmask_b32_e32 v83, v147, v83, vcc
	v_cndmask_b32_e32 v84, v147, v84, vcc
	v_cndmask_b32_e32 v85, v147, v85, vcc
	global_store_dwordx4 v163, v[82:85], s[48:49]
	global_load_dwordx4 v[212:215], v163, s[42:43] offset:512
	v_pk_fma_f32 v[74:75], v[138:139], v[74:75], v[216:217]
	v_pk_fma_f32 v[76:77], v[140:141], v[76:77], v[218:219]
	v_cndmask_b32_e32 v74, v147, v74, vcc
	v_cndmask_b32_e32 v75, v147, v75, vcc
	v_cndmask_b32_e32 v76, v147, v76, vcc
	v_cndmask_b32_e32 v77, v147, v77, vcc
	global_store_dwordx4 v163, v[74:77], s[48:49] offset:64
	global_load_dwordx4 v[216:219], v163, s[42:43] offset:576
	v_pk_fma_f32 v[70:71], v[134:135], v[70:71], v[220:221]
	v_pk_fma_f32 v[72:73], v[136:137], v[72:73], v[222:223]
	v_cndmask_b32_e32 v70, v147, v70, vcc
	v_cndmask_b32_e32 v71, v147, v71, vcc
	v_cndmask_b32_e32 v72, v147, v72, vcc
	v_cndmask_b32_e32 v73, v147, v73, vcc
	global_store_dwordx4 v163, v[70:73], s[48:49] offset:512
	v_pk_fma_f32 v[66:67], v[126:127], v[66:67], v[224:225]
	v_pk_fma_f32 v[68:69], v[128:129], v[68:69], v[226:227]
	v_cndmask_b32_e32 v66, v147, v66, vcc
	v_cndmask_b32_e32 v67, v147, v67, vcc
	v_cndmask_b32_e32 v68, v147, v68, vcc
	v_cndmask_b32_e32 v69, v147, v69, vcc
	global_store_dwordx4 v163, v[66:69], s[48:49] offset:576
	s_waitcnt vmcnt(15)
;     __device__ __forceinline__ void fused(f32x4 (&acc)[2][2][4][2], const Unit& u, int wr, int wc, int fr, int fq, PG8_LAS unsigned char* lds, int wid, int lane) const {
;     ...
; #pragma unroll
;         for (int ai = 0; ai < 2; ++ai)
; #pragma unroll
;             for (int m = 0; m < 4; ++m) { const int r = ai * HALF + wr * 64 + m * 16 + fr; const float rs = S[r]; const size_t off = (size_t)r * 1024 + col0;
; #pragma unroll
;                 for (int bj = 0; bj < 2; ++bj)
; #pragma unroll
;                     for (int n = 0; n < 2; ++n) { const f32x4 xv = *(const f32x4*)(xb + off + bj * HALF + n * 16); f32x4 o = xv + acc[ai][bj][m][n] * rs * gv[bj][n];
;                         if (bad) o = (f32x4){qnan, qnan, qnan, qnan}; *(f32x4*)(ob + off + bj * HALF + n * 16) = o; }
;                 if (m & 1) asm volatile("" ::: "memory"); }
	v_pk_fma_f32 v[62:63], v[142:143], v[62:63], v[228:229]
	v_pk_fma_f32 v[64:65], v[144:145], v[64:65], v[230:231]
	v_cndmask_b32_e32 v62, v147, v62, vcc
	v_cndmask_b32_e32 v63, v147, v63, vcc
	v_cndmask_b32_e32 v64, v147, v64, vcc
	v_cndmask_b32_e32 v65, v147, v65, vcc
	s_waitcnt vmcnt(14)
	v_pk_fma_f32 v[58:59], v[138:139], v[58:59], v[232:233]
	v_pk_fma_f32 v[60:61], v[140:141], v[60:61], v[234:235]
	v_cndmask_b32_e32 v58, v147, v58, vcc
	v_cndmask_b32_e32 v59, v147, v59, vcc
	v_cndmask_b32_e32 v60, v147, v60, vcc
	v_cndmask_b32_e32 v61, v147, v61, vcc
	s_waitcnt vmcnt(13)
	v_pk_fma_f32 v[54:55], v[134:135], v[54:55], v[164:165]
	v_pk_fma_f32 v[56:57], v[136:137], v[56:57], v[166:167]
	v_cndmask_b32_e32 v54, v147, v54, vcc
	v_cndmask_b32_e32 v55, v147, v55, vcc
	v_cndmask_b32_e32 v56, v147, v56, vcc
	v_cndmask_b32_e32 v57, v147, v57, vcc
	s_waitcnt vmcnt(12)
	v_pk_fma_f32 v[46:47], v[126:127], v[46:47], v[168:169]
	v_pk_fma_f32 v[48:49], v[128:129], v[48:49], v[170:171]
	v_cndmask_b32_e32 v46, v147, v46, vcc
	v_cndmask_b32_e32 v47, v147, v47, vcc
	v_cndmask_b32_e32 v48, v147, v48, vcc
	v_cndmask_b32_e32 v49, v147, v49, vcc
	s_waitcnt vmcnt(11)
	v_pk_fma_f32 v[50:51], v[142:143], v[50:51], v[172:173]
	v_pk_fma_f32 v[52:53], v[144:145], v[52:53], v[174:175]
	v_cndmask_b32_e32 v50, v147, v50, vcc
	v_cndmask_b32_e32 v51, v147, v51, vcc
	v_cndmask_b32_e32 v52, v147, v52, vcc
	v_cndmask_b32_e32 v53, v147, v53, vcc
	s_waitcnt vmcnt(10)
	v_pk_fma_f32 v[42:43], v[138:139], v[42:43], v[176:177]
	v_pk_fma_f32 v[44:45], v[140:141], v[44:45], v[178:179]
	v_cndmask_b32_e32 v42, v147, v42, vcc
	v_cndmask_b32_e32 v43, v147, v43, vcc
	v_cndmask_b32_e32 v44, v147, v44, vcc
	v_cndmask_b32_e32 v45, v147, v45, vcc
	s_waitcnt vmcnt(9)
	v_pk_fma_f32 v[38:39], v[134:135], v[38:39], v[180:181]
	v_pk_fma_f32 v[40:41], v[136:137], v[40:41], v[182:183]
	v_cndmask_b32_e32 v38, v147, v38, vcc
	v_cndmask_b32_e32 v39, v147, v39, vcc
	v_cndmask_b32_e32 v40, v147, v40, vcc
	v_cndmask_b32_e32 v41, v147, v41, vcc
	s_waitcnt vmcnt(8)
	v_pk_fma_f32 v[30:31], v[126:127], v[30:31], v[184:185]
	v_pk_fma_f32 v[32:33], v[128:129], v[32:33], v[186:187]
	v_cndmask_b32_e32 v30, v147, v30, vcc
	v_cndmask_b32_e32 v31, v147, v31, vcc
	v_cndmask_b32_e32 v32, v147, v32, vcc
	v_cndmask_b32_e32 v33, v147, v33, vcc
	s_waitcnt vmcnt(7)
	v_pk_fma_f32 v[34:35], v[142:143], v[34:35], v[188:189]
	v_pk_fma_f32 v[36:37], v[144:145], v[36:37], v[190:191]
	v_cndmask_b32_e32 v34, v147, v34, vcc
	v_cndmask_b32_e32 v35, v147, v35, vcc
	v_cndmask_b32_e32 v36, v147, v36, vcc
	v_cndmask_b32_e32 v37, v147, v37, vcc
	s_waitcnt vmcnt(6)
	v_pk_fma_f32 v[26:27], v[138:139], v[26:27], v[192:193]
	v_pk_fma_f32 v[28:29], v[140:141], v[28:29], v[194:195]
	v_cndmask_b32_e32 v26, v147, v26, vcc
	v_cndmask_b32_e32 v27, v147, v27, vcc
	v_cndmask_b32_e32 v28, v147, v28, vcc
	v_cndmask_b32_e32 v29, v147, v29, vcc
	s_waitcnt vmcnt(5)
	v_pk_fma_f32 v[22:23], v[134:135], v[22:23], v[196:197]
	v_pk_fma_f32 v[24:25], v[136:137], v[24:25], v[198:199]
	v_cndmask_b32_e32 v22, v147, v22, vcc
	v_cndmask_b32_e32 v23, v147, v23, vcc
	v_cndmask_b32_e32 v24, v147, v24, vcc
	v_cndmask_b32_e32 v25, v147, v25, vcc
	s_waitcnt vmcnt(4)
	v_pk_fma_f32 v[14:15], v[126:127], v[14:15], v[200:201]
	v_pk_fma_f32 v[16:17], v[128:129], v[16:17], v[202:203]
	v_cndmask_b32_e32 v14, v147, v14, vcc
	v_cndmask_b32_e32 v15, v147, v15, vcc
	v_cndmask_b32_e32 v16, v147, v16, vcc
	v_cndmask_b32_e32 v17, v147, v17, vcc
	s_waitcnt vmcnt(3)
	v_pk_fma_f32 v[18:19], v[142:143], v[18:19], v[204:205]
	v_pk_fma_f32 v[20:21], v[144:145], v[20:21], v[206:207]
	v_cndmask_b32_e32 v18, v147, v18, vcc
	v_cndmask_b32_e32 v19, v147, v19, vcc
	v_cndmask_b32_e32 v20, v147, v20, vcc
	v_cndmask_b32_e32 v21, v147, v21, vcc
	s_waitcnt vmcnt(2)
	v_pk_fma_f32 v[10:11], v[138:139], v[10:11], v[208:209]
	v_pk_fma_f32 v[12:13], v[140:141], v[12:13], v[210:211]
	v_cndmask_b32_e32 v10, v147, v10, vcc
	v_cndmask_b32_e32 v11, v147, v11, vcc
	v_cndmask_b32_e32 v12, v147, v12, vcc
	v_cndmask_b32_e32 v13, v147, v13, vcc
	s_waitcnt vmcnt(1)
	v_pk_fma_f32 v[6:7], v[134:135], v[6:7], v[212:213]
	v_pk_fma_f32 v[8:9], v[136:137], v[8:9], v[214:215]
	v_cndmask_b32_e32 v6, v147, v6, vcc
	v_cndmask_b32_e32 v7, v147, v7, vcc
	v_cndmask_b32_e32 v8, v147, v8, vcc
	v_cndmask_b32_e32 v9, v147, v9, vcc
	s_waitcnt vmcnt(0)
	v_pk_fma_f32 v[2:3], v[126:127], v[2:3], v[216:217]
	v_pk_fma_f32 v[4:5], v[128:129], v[4:5], v[218:219]
	v_cndmask_b32_e32 v2, v147, v2, vcc
	v_cndmask_b32_e32 v3, v147, v3, vcc
	v_cndmask_b32_e32 v4, v147, v4, vcc
	v_cndmask_b32_e32 v5, v147, v5, vcc
	global_store_dwordx4 v163, v[62:65], s[50:51]
	global_store_dwordx4 v163, v[58:61], s[50:51] offset:64
	global_store_dwordx4 v163, v[54:57], s[50:51] offset:512
	global_store_dwordx4 v163, v[46:49], s[50:51] offset:576
	global_store_dwordx4 v163, v[50:53], s[52:53]
	global_store_dwordx4 v163, v[42:45], s[52:53] offset:64
	global_store_dwordx4 v163, v[38:41], s[52:53] offset:512
	global_store_dwordx4 v163, v[30:33], s[52:53] offset:576
	global_store_dwordx4 v163, v[34:37], s[54:55]
	global_store_dwordx4 v163, v[26:29], s[54:55] offset:64
	global_store_dwordx4 v163, v[22:25], s[54:55] offset:512
	global_store_dwordx4 v163, v[14:17], s[54:55] offset:576
	global_store_dwordx4 v163, v[18:21], s[56:57]
	global_store_dwordx4 v163, v[10:13], s[56:57] offset:64
	global_store_dwordx4 v163, v[6:9], s[56:57] offset:512
	global_store_dwordx4 v163, v[2:5], s[56:57] offset:576
	s_endpgm
